# v6 stack plus prologue-B XG0 rows: both halves' loads issued together and DPP plus readlane row sums
# baseline (speedup 1.0000x reference)
.LBB0_142:
	v_lshl_add_u64 v[20:21], v[8:9], 2, s[18:19]
	v_add_co_u32_e32 v0, vcc, s54, v20
	global_load_dwordx4 v[34:37], v[20:21], off offset:16
	global_load_dwordx4 v[38:41], v[20:21], off
	s_waitcnt lgkmcnt(0)
	v_addc_co_u32_e32 v1, vcc, 0, v21, vcc
	v_lshl_add_u64 v[22:23], v[20:21], 0, s[82:83]
	global_load_dwordx4 v[4:7], v[0:1], off
	s_nop 0
	global_load_dwordx4 v[0:3], v[22:23], off offset:16
	global_load_dwordx4 v[42:45], v[12:13], off offset:16
	global_load_dwordx4 v[26:29], v[12:13], off
	global_load_dwordx4 v[46:49], v[16:17], off
	global_load_dwordx4 v[50:53], v[16:17], off offset:16
	s_lshl_b64 s[16:17], s[14:15], 11
	global_load_dwordx4 v[100:103], v[20:21], off offset:2064
	global_load_dwordx4 v[104:107], v[20:21], off offset:2048
	global_load_dwordx4 v[68:71], v[22:23], off offset:2064
	global_load_dwordx4 v[72:75], v[22:23], off offset:2048
	global_load_dwordx4 v[96:99], v[12:13], off offset:2064
	global_load_dwordx4 v[108:111], v[12:13], off offset:2048
	global_load_dwordx4 v[112:115], v[16:17], off offset:2048
	global_load_dwordx4 v[116:119], v[16:17], off offset:2064
	s_waitcnt vmcnt(0)
	v_mul_f32_e32 v33, v37, v37
	v_fmac_f32_e32 v33, v36, v36
	s_waitcnt lgkmcnt(0)
	v_pk_add_f32 v[18:19], v[48:49], 1.0 op_sel_hi:[1,0]
	s_nop 0
	v_pk_mul_f32 v[24:25], v[28:29], v[18:19]
	v_pk_add_f32 v[18:19], v[52:53], 1.0 op_sel_hi:[1,0]
	v_pk_add_f32 v[30:31], v[46:47], 1.0 op_sel_hi:[1,0]
	v_pk_mul_f32 v[28:29], v[44:45], v[18:19]
	v_mul_f32_e32 v18, v39, v39
	v_mul_f32_e32 v19, v41, v41
	v_fmac_f32_e32 v18, v38, v38
	v_fmac_f32_e32 v19, v40, v40
	v_add_f32_e32 v18, v18, v19
	v_mul_f32_e32 v19, v35, v35
	v_fmac_f32_e32 v19, v34, v34
	v_add_f32_e32 v19, v19, v33
	v_add_f32_e32 v33, v18, v19
	v_mul_f32_e32 v18, v5, v5
	v_mul_f32_e32 v19, v7, v7
	v_pk_mul_f32 v[26:27], v[26:27], v[30:31]
	v_pk_add_f32 v[30:31], v[50:51], 1.0 op_sel_hi:[1,0]
	v_fmac_f32_e32 v18, v4, v4
	v_fmac_f32_e32 v19, v6, v6
	v_pk_mul_f32 v[30:31], v[42:43], v[30:31]
	v_add_f32_e32 v18, v18, v19
	v_mul_f32_e32 v19, v1, v1
	v_mul_f32_e32 v42, v3, v3
	v_fmac_f32_e32 v19, v0, v0
	v_fmac_f32_e32 v42, v2, v2
	v_add_f32_e32 v19, v19, v42
	v_add_f32_e32 v46, v18, v19
	v_pk_mul_f32 v[18:19], v[40:41], v[24:25]
	v_pk_mul_f32 v[38:39], v[38:39], v[26:27]
	v_pk_mul_f32 v[34:35], v[34:35], v[30:31]
	v_cvt_pk_bf16_f32 v38, v38, v39
	v_cvt_pk_bf16_f32 v39, v18, v19
	v_pk_mul_f32 v[18:19], v[36:37], v[28:29]
	v_cvt_pk_bf16_f32 v40, v34, v35
	v_cvt_pk_bf16_f32 v41, v18, v19
	v_lshl_add_u64 v[18:19], v[14:15], 0, s[16:17]
	global_store_dwordx4 v[18:19], v[38:41], off sc1
	s_nop 1
	v_pk_mul_f32 v[6:7], v[6:7], v[24:25]
	v_pk_mul_f32 v[4:5], v[4:5], v[26:27]
	v_pk_mul_f32 v[2:3], v[2:3], v[28:29]
	v_pk_mul_f32 v[0:1], v[0:1], v[30:31]
	v_cvt_pk_bf16_f32 v4, v4, v5
	v_cvt_pk_bf16_f32 v5, v6, v7
	v_cvt_pk_bf16_f32 v6, v0, v1
	v_cvt_pk_bf16_f32 v7, v2, v3
	v_lshl_add_u64 v[0:1], v[18:19], 0, s[68:69]
	global_store_dwordx4 v[0:1], v[4:7], off sc1
	s_nop 1
	s_waitcnt lgkmcnt(0)
	v_pk_add_f32 v[114:115], v[114:115], 1.0 op_sel_hi:[1,0]
	s_nop 0
	v_pk_mul_f32 v[110:111], v[110:111], v[114:115]
	v_pk_add_f32 v[114:115], v[116:117], 1.0 op_sel_hi:[1,0]
	v_pk_add_f32 v[112:113], v[112:113], 1.0 op_sel_hi:[1,0]
	v_pk_mul_f32 v[114:115], v[96:97], v[114:115]
	v_mul_f32_e32 v96, v105, v105
	v_mul_f32_e32 v97, v107, v107
	v_pk_mul_f32 v[108:109], v[108:109], v[112:113]
	v_pk_add_f32 v[112:113], v[118:119], 1.0 op_sel_hi:[1,0]
	v_fmac_f32_e32 v96, v104, v104
	v_fmac_f32_e32 v97, v106, v106
	v_pk_mul_f32 v[112:113], v[98:99], v[112:113]
	v_add_f32_e32 v96, v96, v97
	v_mul_f32_e32 v97, v101, v101
	v_mul_f32_e32 v98, v103, v103
	v_fmac_f32_e32 v97, v100, v100
	v_fmac_f32_e32 v98, v102, v102
	v_add_f32_e32 v97, v97, v98
	v_add_f32_e32 v96, v96, v97
	v_add_f32_e32 v97, v33, v96
	v_mul_f32_e32 v96, v73, v73
	v_mul_f32_e32 v98, v75, v75
	v_fmac_f32_e32 v96, v72, v72
	v_fmac_f32_e32 v98, v74, v74
	v_add_f32_e32 v96, v96, v98
	v_mul_f32_e32 v98, v69, v69
	v_mul_f32_e32 v99, v71, v71
	v_fmac_f32_e32 v98, v68, v68
	v_fmac_f32_e32 v99, v70, v70
	v_add_f32_e32 v98, v98, v99
	v_add_f32_e32 v96, v96, v98
	v_pk_mul_f32 v[106:107], v[106:107], v[110:111]
	v_pk_mul_f32 v[98:99], v[104:105], v[108:109]
	v_pk_mul_f32 v[102:103], v[102:103], v[112:113]
	v_pk_mul_f32 v[100:101], v[100:101], v[114:115]
	v_pk_mul_f32 v[74:75], v[74:75], v[110:111]
	v_pk_mul_f32 v[72:73], v[72:73], v[108:109]
	v_pk_mul_f32 v[68:69], v[68:69], v[114:115]
	v_add_f32_e32 v96, v46, v96
	v_cvt_pk_bf16_f32 v98, v98, v99
	v_cvt_pk_bf16_f32 v99, v106, v107
	v_cvt_pk_bf16_f32 v100, v100, v101
	v_cvt_pk_bf16_f32 v101, v102, v103
	v_lshl_add_u64 v[102:103], v[18:19], 0, s[24:25]
	global_store_dwordx4 v[102:103], v[98:101], off sc1
	s_nop 1
	v_cvt_pk_bf16_f32 v72, v72, v73
	v_cvt_pk_bf16_f32 v73, v74, v75
	v_pk_mul_f32 v[70:71], v[70:71], v[112:113]
	v_cvt_pk_bf16_f32 v74, v68, v69
	v_lshl_add_u64 v[68:69], v[18:19], 0, s[56:57]
	v_cvt_pk_bf16_f32 v75, v70, v71
	global_store_dwordx4 v[68:69], v[72:75], off sc1
	s_nop 1
	s_nop 0
	v_add_f32_dpp v97, v97, v97 quad_perm:[1,0,3,2] row_mask:0xf bank_mask:0xf
	v_add_f32_dpp v96, v96, v96 quad_perm:[1,0,3,2] row_mask:0xf bank_mask:0xf
	s_nop 0
	v_add_f32_dpp v97, v97, v97 quad_perm:[2,3,0,1] row_mask:0xf bank_mask:0xf
	v_add_f32_dpp v96, v96, v96 quad_perm:[2,3,0,1] row_mask:0xf bank_mask:0xf
	s_nop 0
	v_add_f32_dpp v97, v97, v97 row_half_mirror row_mask:0xf bank_mask:0xf
	v_add_f32_dpp v96, v96, v96 row_half_mirror row_mask:0xf bank_mask:0xf
	s_nop 0
	v_add_f32_dpp v97, v97, v97 row_mirror row_mask:0xf bank_mask:0xf
	v_add_f32_dpp v96, v96, v96 row_mirror row_mask:0xf bank_mask:0xf
	s_nop 1
	v_readlane_b32 s100, v97, 0
	v_readlane_b32 s101, v97, 16
	s_nop 1
	v_mov_b32_e32 v0, s100
	v_add_f32_e32 v0, s101, v0
	v_readlane_b32 s100, v97, 32
	v_readlane_b32 s101, v97, 48
	s_nop 1
	v_add_f32_e32 v0, s100, v0
	v_add_f32_e32 v0, s101, v0
	v_readlane_b32 s100, v96, 0
	v_readlane_b32 s101, v96, 16
	s_nop 1
	v_mov_b32_e32 v2, s100
	v_add_f32_e32 v2, s101, v2
	v_readlane_b32 s100, v96, 32
	v_readlane_b32 s101, v96, 48
	s_nop 1
	v_add_f32_e32 v2, s100, v2
	v_add_f32_e32 v2, s101, v2
	s_and_saveexec_b64 s[16:17], s[38:39]
	s_cbranch_execz .LBB0_137
	v_cndmask_b32_e64 v0, v2, v0, s[42:43]
	v_cndmask_b32_e64 v2, 0, v0, s[40:41]
	v_add_u32_e32 v0, s14, v32
	v_ashrrev_i32_e32 v1, 31, v0
	v_lshlrev_b64 v[0:1], 6, v[0:1]
	v_lshl_add_u64 v[0:1], v[10:11], 0, v[0:1]
	global_store_dword v[0:1], v2, off sc1
	s_branch .LBB0_137
